# v132 + nt on residual x loads and stores in EpiRes epilogue
# speedup vs baseline: 1.0058x; 1.0058x over previous
.LBB0_519:
	s_min_i32 s25, s47, 0x80
	s_lshr_b32 s25, s25, 4
	s_mul_i32 s40, s25, 0x1800
	s_ashr_i32 s41, s40, 31
	s_lshl_b64 s[40:41], s[40:41], 2
	s_add_u32 s42, s18, s40
	s_addc_u32 s43, s19, s41
	s_cmpk_lt_i32 s47, 0x80
	v_lshl_add_u32 v146, s47, 18, v143
	v_add_u32_e32 v0, 0xfe000000, v146
	s_cselect_b64 vcc, -1, 0
	v_lshl_or_b32 v140, s46, 8, v144
	v_cndmask_b32_e32 v147, v0, v146, vcc
	s_and_b64 s[40:41], vcc, exec
	v_add_u32_e32 v0, v147, v140
	s_cselect_b32 s41, s15, s55
	s_cselect_b32 s40, s16, s54
	v_lshlrev_b64 v[152:153], 2, v[0:1]
	v_mov_b32_e32 v141, v1
	v_lshl_add_u64 v[146:147], s[40:41], 0, v[152:153]
	v_lshl_add_u64 v[138:139], v[140:141], 2, s[42:43]
	global_load_dwordx4 v[172:175], v[138:139], off
	global_load_dwordx4 v[176:179], v[138:139], off offset:64
	global_load_dwordx4 v[180:183], v[138:139], off offset:512
	global_load_dwordx4 v[184:187], v[138:139], off offset:576
	v_readlane_b32 s56, v254, 4
	v_readlane_b32 s70, v254, 18
	v_readlane_b32 s71, v254, 19
	s_cselect_b32 s43, s71, s55
	s_cselect_b32 s42, s70, s54
	v_lshl_add_u64 v[152:153], s[42:43], 0, v[152:153]
	v_readlane_b32 s57, v254, 5
	v_readlane_b32 s58, v254, 6
	v_readlane_b32 s59, v254, 7
	v_readlane_b32 s60, v254, 8
	v_readlane_b32 s61, v254, 9
	v_readlane_b32 s62, v254, 10
	v_readlane_b32 s63, v254, 11
	v_readlane_b32 s64, v254, 12
	v_readlane_b32 s65, v254, 13
	v_readlane_b32 s66, v254, 14
	v_readlane_b32 s67, v254, 15
	v_readlane_b32 s68, v254, 16
	v_readlane_b32 s69, v254, 17
	s_mov_b64 s[40:41], 0x10000
	s_mov_b64 s[42:43], 0x50000
	global_load_dwordx4 v[148:151], v[146:147], off nt
	global_load_dwordx4 v[168:171], v[146:147], off offset:64 nt
	global_load_dwordx4 v[188:191], v[146:147], off offset:512 nt
	global_load_dwordx4 v[192:195], v[146:147], off offset:576 nt
	v_lshl_add_u64 v[146:147], v[146:147], 0, s[40:41]
	global_load_dwordx4 v[196:199], v[146:147], off nt
	global_load_dwordx4 v[200:203], v[146:147], off offset:64 nt
	global_load_dwordx4 v[204:207], v[146:147], off offset:512 nt
	global_load_dwordx4 v[208:211], v[146:147], off offset:576 nt
	v_lshl_add_u64 v[146:147], v[146:147], 0, s[40:41]
	global_load_dwordx4 v[212:215], v[146:147], off nt
	global_load_dwordx4 v[224:227], v[146:147], off offset:64 nt
	global_load_dwordx4 v[234:237], v[146:147], off offset:512 nt
	global_load_dwordx4 v[238:241], v[146:147], off offset:576 nt
	s_waitcnt vmcnt(11)
	v_pk_fma_f32 v[128:129], v[128:129], v[174:175], v[150:151]
	v_pk_fma_f32 v[126:127], v[126:127], v[172:173], v[148:149]
	global_store_dwordx4 v[152:153], v[126:129], off nt
	v_lshl_add_u64 v[146:147], v[146:147], 0, s[40:41]
	global_load_dwordx4 v[148:151], v[146:147], off nt
	s_waitcnt vmcnt(12)
	v_pk_fma_f32 v[124:125], v[124:125], v[178:179], v[170:171]
	v_pk_fma_f32 v[122:123], v[122:123], v[176:177], v[168:169]
	global_store_dwordx4 v[152:153], v[122:125], off offset:64 nt
	global_load_dwordx4 v[168:171], v[146:147], off offset:64 nt
	s_waitcnt vmcnt(13)
	v_pk_fma_f32 v[120:121], v[120:121], v[182:183], v[190:191]
	v_pk_fma_f32 v[118:119], v[118:119], v[180:181], v[188:189]
	global_store_dwordx4 v[152:153], v[118:121], off offset:512 nt
	global_load_dwordx4 v[188:191], v[146:147], off offset:512 nt
	s_waitcnt vmcnt(14)
	v_pk_fma_f32 v[112:113], v[112:113], v[186:187], v[194:195]
	v_pk_fma_f32 v[110:111], v[110:111], v[184:185], v[192:193]
	global_store_dwordx4 v[152:153], v[110:113], off offset:576 nt
	global_load_dwordx4 v[192:195], v[146:147], off offset:576 nt
	s_waitcnt vmcnt(15)
	v_pk_fma_f32 v[116:117], v[116:117], v[174:175], v[198:199]
	v_pk_fma_f32 v[114:115], v[114:115], v[172:173], v[196:197]
	v_lshl_add_u64 v[152:153], v[152:153], 0, s[40:41]
	global_store_dwordx4 v[152:153], v[114:117], off nt
	v_lshl_add_u64 v[146:147], v[146:147], 0, s[42:43]
	global_load_dwordx4 v[196:199], v[146:147], off nt
	s_waitcnt vmcnt(16)
	v_pk_fma_f32 v[108:109], v[108:109], v[178:179], v[202:203]
	v_pk_fma_f32 v[106:107], v[106:107], v[176:177], v[200:201]
	global_store_dwordx4 v[152:153], v[106:109], off offset:64 nt
	global_load_dwordx4 v[200:203], v[146:147], off offset:64 nt
	s_waitcnt vmcnt(17)
	v_pk_fma_f32 v[104:105], v[104:105], v[182:183], v[206:207]
	v_pk_fma_f32 v[102:103], v[102:103], v[180:181], v[204:205]
	global_store_dwordx4 v[152:153], v[102:105], off offset:512 nt
	global_load_dwordx4 v[204:207], v[146:147], off offset:512 nt
	s_waitcnt vmcnt(18)
	v_pk_fma_f32 v[96:97], v[96:97], v[186:187], v[210:211]
	v_pk_fma_f32 v[94:95], v[94:95], v[184:185], v[208:209]
	global_store_dwordx4 v[152:153], v[94:97], off offset:576 nt
	global_load_dwordx4 v[208:211], v[146:147], off offset:576 nt
	s_waitcnt vmcnt(19)
	v_pk_fma_f32 v[100:101], v[100:101], v[174:175], v[214:215]
	v_pk_fma_f32 v[98:99], v[98:99], v[172:173], v[212:213]
	v_lshl_add_u64 v[152:153], v[152:153], 0, s[40:41]
	global_store_dwordx4 v[152:153], v[98:101], off nt
	v_lshl_add_u64 v[146:147], v[146:147], 0, s[40:41]
	global_load_dwordx4 v[212:215], v[146:147], off nt
	s_waitcnt vmcnt(20)
	v_pk_fma_f32 v[92:93], v[92:93], v[178:179], v[226:227]
	v_pk_fma_f32 v[90:91], v[90:91], v[176:177], v[224:225]
	global_store_dwordx4 v[152:153], v[90:93], off offset:64 nt
	global_load_dwordx4 v[224:227], v[146:147], off offset:64 nt
	s_waitcnt vmcnt(21)
	v_pk_fma_f32 v[88:89], v[88:89], v[182:183], v[236:237]
	v_pk_fma_f32 v[86:87], v[86:87], v[180:181], v[234:235]
	global_store_dwordx4 v[152:153], v[86:89], off offset:512 nt
	global_load_dwordx4 v[234:237], v[146:147], off offset:512 nt
	s_waitcnt vmcnt(22)
	v_pk_fma_f32 v[80:81], v[80:81], v[186:187], v[240:241]
	v_pk_fma_f32 v[78:79], v[78:79], v[184:185], v[238:239]
	global_store_dwordx4 v[152:153], v[78:81], off offset:576 nt
	global_load_dwordx4 v[238:241], v[146:147], off offset:576 nt
	s_waitcnt vmcnt(22)
	v_pk_fma_f32 v[84:85], v[84:85], v[174:175], v[150:151]
	v_pk_fma_f32 v[82:83], v[82:83], v[172:173], v[148:149]
	v_lshl_add_u64 v[152:153], v[152:153], 0, s[40:41]
	global_store_dwordx4 v[152:153], v[82:85], off nt
	v_lshl_add_u64 v[146:147], v[146:147], 0, s[40:41]
	global_load_dwordx4 v[148:151], v[146:147], off nt
	s_waitcnt vmcnt(22)
	v_pk_fma_f32 v[76:77], v[76:77], v[178:179], v[170:171]
	v_pk_fma_f32 v[74:75], v[74:75], v[176:177], v[168:169]
	global_store_dwordx4 v[152:153], v[74:77], off offset:64 nt
	global_load_dwordx4 v[168:171], v[146:147], off offset:64 nt
	s_waitcnt vmcnt(22)
	v_pk_fma_f32 v[72:73], v[72:73], v[182:183], v[190:191]
	v_pk_fma_f32 v[70:71], v[70:71], v[180:181], v[188:189]
	global_store_dwordx4 v[152:153], v[70:73], off offset:512 nt
	global_load_dwordx4 v[188:191], v[146:147], off offset:512 nt
	s_waitcnt vmcnt(22)
	v_pk_fma_f32 v[68:69], v[68:69], v[186:187], v[194:195]
	v_pk_fma_f32 v[66:67], v[66:67], v[184:185], v[192:193]
	global_store_dwordx4 v[152:153], v[66:69], off offset:576 nt
	global_load_dwordx4 v[192:195], v[146:147], off offset:576 nt
	s_waitcnt vmcnt(22)
	v_pk_fma_f32 v[64:65], v[64:65], v[174:175], v[198:199]
	v_pk_fma_f32 v[62:63], v[62:63], v[172:173], v[196:197]
	v_lshl_add_u64 v[152:153], v[152:153], 0, s[42:43]
	global_store_dwordx4 v[152:153], v[62:65], off nt
	v_lshl_add_u64 v[146:147], v[146:147], 0, s[40:41]
	global_load_dwordx4 v[196:199], v[146:147], off nt
	s_waitcnt vmcnt(22)
	v_pk_fma_f32 v[60:61], v[60:61], v[178:179], v[202:203]
	v_pk_fma_f32 v[58:59], v[58:59], v[176:177], v[200:201]
	global_store_dwordx4 v[152:153], v[58:61], off offset:64 nt
	global_load_dwordx4 v[200:203], v[146:147], off offset:64 nt
	s_waitcnt vmcnt(22)
	v_pk_fma_f32 v[56:57], v[56:57], v[182:183], v[206:207]
	v_pk_fma_f32 v[54:55], v[54:55], v[180:181], v[204:205]
	global_store_dwordx4 v[152:153], v[54:57], off offset:512 nt
	global_load_dwordx4 v[204:207], v[146:147], off offset:512 nt
	s_waitcnt vmcnt(22)
	v_pk_fma_f32 v[48:49], v[48:49], v[186:187], v[210:211]
	v_pk_fma_f32 v[46:47], v[46:47], v[184:185], v[208:209]
	global_store_dwordx4 v[152:153], v[46:49], off offset:576 nt
	global_load_dwordx4 v[208:211], v[146:147], off offset:576 nt
	s_waitcnt vmcnt(22)
	v_pk_fma_f32 v[52:53], v[52:53], v[174:175], v[214:215]
	v_pk_fma_f32 v[50:51], v[50:51], v[172:173], v[212:213]
	v_lshl_add_u64 v[152:153], v[152:153], 0, s[40:41]
	global_store_dwordx4 v[152:153], v[50:53], off nt
	s_waitcnt vmcnt(21)
	v_pk_fma_f32 v[44:45], v[44:45], v[178:179], v[226:227]
	v_pk_fma_f32 v[42:43], v[42:43], v[176:177], v[224:225]
	global_store_dwordx4 v[152:153], v[42:45], off offset:64 nt
	s_waitcnt vmcnt(20)
	v_pk_fma_f32 v[40:41], v[40:41], v[182:183], v[236:237]
	v_pk_fma_f32 v[38:39], v[38:39], v[180:181], v[234:235]
	global_store_dwordx4 v[152:153], v[38:41], off offset:512 nt
	s_waitcnt vmcnt(19)
	v_pk_fma_f32 v[32:33], v[32:33], v[186:187], v[240:241]
	v_pk_fma_f32 v[30:31], v[30:31], v[184:185], v[238:239]
	global_store_dwordx4 v[152:153], v[30:33], off offset:576 nt
	s_waitcnt vmcnt(18)
	v_pk_fma_f32 v[36:37], v[36:37], v[174:175], v[150:151]
	v_pk_fma_f32 v[34:35], v[34:35], v[172:173], v[148:149]
	v_lshl_add_u64 v[152:153], v[152:153], 0, s[40:41]
	global_store_dwordx4 v[152:153], v[34:37], off nt
	s_waitcnt vmcnt(17)
	v_pk_fma_f32 v[28:29], v[28:29], v[178:179], v[170:171]
	v_pk_fma_f32 v[26:27], v[26:27], v[176:177], v[168:169]
	global_store_dwordx4 v[152:153], v[26:29], off offset:64 nt
	s_waitcnt vmcnt(16)
	v_pk_fma_f32 v[24:25], v[24:25], v[182:183], v[190:191]
	v_pk_fma_f32 v[22:23], v[22:23], v[180:181], v[188:189]
	global_store_dwordx4 v[152:153], v[22:25], off offset:512 nt
	s_waitcnt vmcnt(15)
	v_pk_fma_f32 v[16:17], v[16:17], v[186:187], v[194:195]
	v_pk_fma_f32 v[14:15], v[14:15], v[184:185], v[192:193]
	global_store_dwordx4 v[152:153], v[14:17], off offset:576 nt
	s_waitcnt vmcnt(14)
	v_pk_fma_f32 v[20:21], v[20:21], v[174:175], v[198:199]
	v_pk_fma_f32 v[18:19], v[18:19], v[172:173], v[196:197]
	v_lshl_add_u64 v[152:153], v[152:153], 0, s[40:41]
	global_store_dwordx4 v[152:153], v[18:21], off nt
	s_waitcnt vmcnt(13)
	v_pk_fma_f32 v[12:13], v[12:13], v[178:179], v[202:203]
	v_pk_fma_f32 v[10:11], v[10:11], v[176:177], v[200:201]
	global_store_dwordx4 v[152:153], v[10:13], off offset:64 nt
	s_waitcnt vmcnt(12)
	v_pk_fma_f32 v[8:9], v[8:9], v[182:183], v[206:207]
	v_pk_fma_f32 v[6:7], v[6:7], v[180:181], v[204:205]
	global_store_dwordx4 v[152:153], v[6:9], off offset:512 nt
	s_waitcnt vmcnt(11)
	v_pk_fma_f32 v[4:5], v[4:5], v[186:187], v[210:211]
	v_pk_fma_f32 v[2:3], v[2:3], v[184:185], v[208:209]
	global_store_dwordx4 v[152:153], v[2:5], off offset:576 nt
	s_andn2_b64 vcc, exec, s[38:39]
	s_mov_b64 s[38:39], -1
	s_cbranch_vccnz .LBB0_508
	s_andn2_b64 vcc, exec, s[2:3]
	s_cbranch_vccnz .LBB0_507
	s_barrier
	s_branch .LBB0_507
